# RESID epilogue: second-half residual rows requested together with the first half (v210-249), consumed later via moves
# speedup vs baseline: 1.0034x; 1.0005x over previous
; DI u32x4 pk8(f32x4 a, f32x4 b) { u32x4 o; o.x = pk2(a.x, a.y); o.y = pk2(a.z, a.w); o.z = pk2(b.x, b.y); o.w = pk2(b.z, b.w); return o; }
; #define EPI_SCHED() __builtin_amdgcn_sched_barrier(0)
;     DI void operator()(const AccT& acc, const Unit& u, int wr, int wc, int fr, int fq) const {
;     ...
; #pragma unroll
;         for (int ai = 0; ai < 2; ++ai) {
;             EPI_SCHED();
;             u32x4 hv[4][2];
; #pragma unroll
;             for (int m = 0; m < 4; ++m)
; #pragma unroll
;                 for (int bj = 0; bj < 2; ++bj) hv[m][bj] = *(const u32x4*)(hb + (row0 + ai * 128 + m * 16) * D + col0 + bj * 128);
; #pragma unroll
;             for (int m = 0; m < 4; ++m) {
;                 const size_t row = row0 + ai * 128 + m * 16;
;                 float sq = 0.f;
; #pragma unroll
;                 for (int bj = 0; bj < 2; ++bj) {
;                     const u32x4 w = hv[m][bj];
;                     f32x4 a, b;
;                     a.x = __uint_as_float(w.x << 16); a.y = __uint_as_float(w.x & 0xffff0000u); a.z = __uint_as_float(w.y << 16); a.w = __uint_as_float(w.y & 0xffff0000u);
;                     b.x = __uint_as_float(w.z << 16); b.y = __uint_as_float(w.z & 0xffff0000u); b.z = __uint_as_float(w.w << 16); b.w = __uint_as_float(w.w & 0xffff0000u);
;                     a += acc[ai][bj][m][0] * alpha; b += acc[ai][bj][m][1] * alpha;
;                     sq += (a.x * a.x + a.y * a.y) + (a.z * a.z + a.w * a.w) + (b.x * b.x + b.y * b.y) + (b.z * b.z + b.w * b.w);
;                     *(u32x4*)(hb + row * D + col0 + bj * 128) = pk8(a, b);
;                 }
;                 sq += __shfl_xor(sq, 16); sq += __shfl_xor(sq, 32);
;                 if (fq == 0) ss[row * 16 + u.pn * 4 + wc] = sq;
.LBB0_2953:
	s_mov_b32 s23, -1
	s_nop 0
	v_mbcnt_lo_u32_b32 v130, s23, 0
	v_mbcnt_hi_u32_b32 v130, s23, v130
	s_ashr_i32 s23, s22, 31
	s_lshl_b64 s[22:23], s[22:23], 8
	s_add_u32 s22, s22, s49
	s_addc_u32 s23, s23, s56
	v_and_or_b32 v156, v130, 15, s22
	s_lshl_b32 s22, s64, 8
	v_ashrrev_i32_e32 v131, 1, v130
	s_or_b32 s22, s22, s50
	v_and_b32_e32 v131, -8, v131
	v_add_u32_e32 v154, s22, v131
	v_xor_b32_e32 v131, 16, v207
	v_cmp_lt_i32_e32 vcc, v131, v222
	s_lshl_b32 s22, s64, 2
	v_mov_b32_e32 v157, s23
	v_cndmask_b32_e32 v131, v207, v131, vcc
	v_cmp_lt_i32_e32 vcc, v223, v222
	v_lshlrev_b32_e32 v178, 2, v131
	v_ashrrev_i32_e32 v155, 31, v154
	v_cndmask_b32_e32 v131, v207, v223, vcc
	v_lshlrev_b32_e32 v177, 2, v131
	v_cmp_gt_u32_e32 vcc, 16, v130
	s_ashr_i32 s23, s22, 31
	v_lshlrev_b64 v[188:189], 1, v[154:155]
	v_lshl_add_u64 v[158:159], s[8:9], 0, v[188:189]
	v_lshlrev_b64 v[190:191], 11, v[156:157]
	v_lshl_add_u64 v[130:131], v[158:159], 0, v[190:191]
	flat_load_dwordx4 v[180:183], v[130:131]
	flat_load_dwordx4 v[184:187], v[130:131] offset:256
	v_or_b32_e32 v168, 16, v156
	v_mov_b32_e32 v169, v157
	v_lshlrev_b64 v[170:171], 11, v[168:169]
	v_or_b32_e32 v164, 32, v156
	v_mov_b32_e32 v165, v157
	v_lshl_add_u64 v[130:131], v[158:159], 0, v[170:171]
	v_lshlrev_b64 v[166:167], 11, v[164:165]
	v_or_b32_e32 v160, 48, v156
	v_mov_b32_e32 v161, v157
	flat_load_dwordx4 v[150:153], v[130:131]
	flat_load_dwordx4 v[146:149], v[130:131] offset:256
	v_lshl_add_u64 v[130:131], v[158:159], 0, v[166:167]
	v_lshlrev_b64 v[162:163], 11, v[160:161]
	flat_load_dwordx4 v[142:145], v[130:131]
	flat_load_dwordx4 v[138:141], v[130:131] offset:256
	v_lshl_add_u64 v[130:131], v[158:159], 0, v[162:163]
	flat_load_dwordx4 v[134:137], v[130:131]
	s_nop 0
	flat_load_dwordx4 v[130:133], v[130:131] offset:256
	v_mov_b32_e32 v252, 0x40000
	v_mov_b32_e32 v253, 0
	v_lshl_add_u64 v[252:253], v[158:159], 0, v[252:253]
	v_lshl_add_u64 v[250:251], v[252:253], 0, v[190:191]
	flat_load_dwordx4 v[210:213], v[250:251]
	flat_load_dwordx4 v[214:217], v[250:251] offset:256
	v_lshl_add_u64 v[250:251], v[252:253], 0, v[170:171]
	flat_load_dwordx4 v[218:221], v[250:251]
	flat_load_dwordx4 v[224:227], v[250:251] offset:256
	v_lshl_add_u64 v[250:251], v[252:253], 0, v[166:167]
	flat_load_dwordx4 v[234:237], v[250:251]
	flat_load_dwordx4 v[238:241], v[250:251] offset:256
	v_lshl_add_u64 v[250:251], v[252:253], 0, v[162:163]
	flat_load_dwordx4 v[242:245], v[250:251]
	flat_load_dwordx4 v[246:249], v[250:251] offset:256
	s_waitcnt vmcnt(8) lgkmcnt(0)
	v_lshlrev_b32_e32 v192, 16, v180
	v_and_b32_e32 v193, 0xffff0000, v180
	v_lshlrev_b32_e32 v180, 16, v181
	v_and_b32_e32 v181, 0xffff0000, v181
	v_lshlrev_b32_e32 v194, 16, v182
	v_and_b32_e32 v195, 0xffff0000, v182
	v_lshlrev_b32_e32 v182, 16, v183
	v_and_b32_e32 v183, 0xffff0000, v183
	v_pk_fma_f32 v[128:129], s[14:15], v[128:129], v[180:181]
	v_pk_fma_f32 v[126:127], s[4:5], v[126:127], v[192:193]
	v_pk_fma_f32 v[180:181], s[14:15], v[124:125], v[182:183]
	v_mul_f32_e32 v124, v127, v127
	v_mul_f32_e32 v125, v129, v129
	v_pk_fma_f32 v[122:123], s[4:5], v[122:123], v[194:195]
	v_fmac_f32_e32 v124, v126, v126
	v_fmac_f32_e32 v125, v128, v128
	v_add_f32_e32 v124, v124, v125
	v_mul_f32_e32 v125, v123, v123
	v_fmac_f32_e32 v125, v122, v122
	v_add_f32_e32 v124, v125, v124
	v_mul_f32_e32 v125, v181, v181
	v_fmac_f32_e32 v125, v180, v180
	v_add_f32_e32 v179, v125, v124
	v_cvt_pk_bf16_f32 v124, v126, v127
	v_cvt_pk_bf16_f32 v126, v122, v123
	v_lshl_add_u64 v[122:123], s[8:9], 0, v[190:191]
	v_cvt_pk_bf16_f32 v125, v128, v129
	v_cvt_pk_bf16_f32 v127, v180, v181
	v_lshl_add_u64 v[122:123], v[122:123], 0, v[188:189]
	flat_store_dwordx4 v[122:123], v[124:127]
	v_lshlrev_b32_e32 v128, 16, v186
	v_and_b32_e32 v129, 0xffff0000, v186
	v_lshlrev_b32_e32 v124, 16, v184
	v_and_b32_e32 v125, 0xffff0000, v184
	v_lshlrev_b32_e32 v126, 16, v185
	v_and_b32_e32 v127, 0xffff0000, v185
	v_lshlrev_b32_e32 v180, 16, v187
	v_and_b32_e32 v181, 0xffff0000, v187
	v_pk_fma_f32 v[120:121], s[14:15], v[120:121], v[126:127]
	v_pk_fma_f32 v[118:119], s[4:5], v[118:119], v[124:125]
	v_pk_fma_f32 v[124:125], s[14:15], v[116:117], v[180:181]
	v_pk_fma_f32 v[116:117], s[4:5], v[114:115], v[128:129]
	v_mul_f32_e32 v114, v119, v119
	v_mul_f32_e32 v115, v121, v121
	v_fmac_f32_e32 v114, v118, v118
	v_fmac_f32_e32 v115, v120, v120
	v_add_f32_e32 v114, v114, v115
	v_mul_f32_e32 v115, v117, v117
	v_fmac_f32_e32 v115, v116, v116
	v_add_f32_e32 v114, v115, v114
	v_mul_f32_e32 v115, v125, v125
	v_fmac_f32_e32 v115, v124, v124
	v_add_f32_e32 v114, v115, v114
	v_add_f32_e32 v126, v179, v114
	v_cvt_pk_bf16_f32 v114, v118, v119
	v_cvt_pk_bf16_f32 v115, v120, v121
	v_cvt_pk_bf16_f32 v116, v116, v117
	v_cvt_pk_bf16_f32 v117, v124, v125
	flat_store_dwordx4 v[122:123], v[114:117] offset:256
	ds_bpermute_b32 v114, v178, v126
	s_waitcnt lgkmcnt(0)
	v_add_f32_e32 v114, v126, v114
	ds_bpermute_b32 v115, v177, v114
	s_and_saveexec_b64 s[24:25], vcc
	s_cbranch_execz .LBB0_2955
	v_lshlrev_b64 v[116:117], 6, v[156:157]
	v_lshl_add_u64 v[116:117], s[12:13], 0, v[116:117]
	v_lshl_add_u64 v[116:117], s[22:23], 2, v[116:117]
	s_lshl_b32 s96, s47, 2
	v_lshl_add_u64 v[116:117], v[116:117], 0, s[96:97]
	s_waitcnt lgkmcnt(0)
	v_add_f32_e32 v114, v114, v115
	flat_store_dword v[116:117], v114

; DI u32x4 pk8(f32x4 a, f32x4 b) { u32x4 o; o.x = pk2(a.x, a.y); o.y = pk2(a.z, a.w); o.z = pk2(b.x, b.y); o.w = pk2(b.z, b.w); return o; }
; #define EPI_SCHED() __builtin_amdgcn_sched_barrier(0)
;     DI void operator()(const AccT& acc, const Unit& u, int wr, int wc, int fr, int fq) const {
;     ...
;         for (int ai = 0; ai < 2; ++ai) {
;             EPI_SCHED();
;             u32x4 hv[4][2];
; #pragma unroll
;             for (int m = 0; m < 4; ++m)
; #pragma unroll
;                 for (int bj = 0; bj < 2; ++bj) hv[m][bj] = *(const u32x4*)(hb + (row0 + ai * 128 + m * 16) * D + col0 + bj * 128);
; #pragma unroll
;             for (int m = 0; m < 4; ++m) {
;                 const size_t row = row0 + ai * 128 + m * 16;
;                 float sq = 0.f;
; #pragma unroll
;                 for (int bj = 0; bj < 2; ++bj) {
;                     const u32x4 w = hv[m][bj];
;                     f32x4 a, b;
;                     a.x = __uint_as_float(w.x << 16); a.y = __uint_as_float(w.x & 0xffff0000u); a.z = __uint_as_float(w.y << 16); a.w = __uint_as_float(w.y & 0xffff0000u);
;                     b.x = __uint_as_float(w.z << 16); b.y = __uint_as_float(w.z & 0xffff0000u); b.z = __uint_as_float(w.w << 16); b.w = __uint_as_float(w.w & 0xffff0000u);
;                     a += acc[ai][bj][m][0] * alpha; b += acc[ai][bj][m][1] * alpha;
;                     sq += (a.x * a.x + a.y * a.y) + (a.z * a.z + a.w * a.w) + (b.x * b.x + b.y * b.y) + (b.z * b.z + b.w * b.w);
;                     *(u32x4*)(hb + row * D + col0 + bj * 128) = pk8(a, b);
;                 }
;                 sq += __shfl_xor(sq, 16); sq += __shfl_xor(sq, 32);
;                 if (fq == 0) ss[row * 16 + u.pn * 4 + wc] = sq;
.LBB0_2961:
	s_or_b64 exec, exec, s[24:25]
	v_lshl_add_u64 v[102:103], v[156:157], 0, s[58:59]
	v_lshlrev_b64 v[112:113], 11, v[102:103]
	s_waitcnt lgkmcnt(0)
	v_lshl_add_u64 v[66:67], v[158:159], 0, v[112:113]
	s_mov_b64 s[24:25], 0x90
	v_lshl_add_u64 v[98:99], v[156:157], 0, s[24:25]
	s_mov_b64 s[24:25], 0xa0
	v_lshlrev_b64 v[100:101], 11, v[98:99]
	v_lshl_add_u64 v[94:95], v[156:157], 0, s[24:25]
	s_mov_b64 s[24:25], 0xb0
	v_lshl_add_u64 v[66:67], v[158:159], 0, v[100:101]
	v_lshlrev_b64 v[96:97], 11, v[94:95]
	v_lshl_add_u64 v[90:91], v[156:157], 0, s[24:25]
	v_lshl_add_u64 v[66:67], v[158:159], 0, v[96:97]
	v_lshlrev_b64 v[92:93], 11, v[90:91]
	v_lshl_add_u64 v[66:67], v[158:159], 0, v[92:93]
	s_nop 0
	s_waitcnt vmcnt(0) lgkmcnt(0)
	v_mov_b64_e32 v[104:105], v[210:211]
	v_mov_b64_e32 v[106:107], v[212:213]
	v_mov_b64_e32 v[108:109], v[214:215]
	v_mov_b64_e32 v[110:111], v[216:217]
	v_mov_b64_e32 v[86:87], v[218:219]
	v_mov_b64_e32 v[88:89], v[220:221]
	v_mov_b64_e32 v[82:83], v[224:225]
	v_mov_b64_e32 v[84:85], v[226:227]
	v_mov_b64_e32 v[78:79], v[234:235]
	v_mov_b64_e32 v[80:81], v[236:237]
	v_mov_b64_e32 v[74:75], v[238:239]
	v_mov_b64_e32 v[76:77], v[240:241]
	v_mov_b64_e32 v[70:71], v[242:243]
	v_mov_b64_e32 v[72:73], v[244:245]
	v_mov_b64_e32 v[66:67], v[246:247]
	v_mov_b64_e32 v[68:69], v[248:249]
	v_lshlrev_b32_e32 v114, 16, v104
	v_and_b32_e32 v115, 0xffff0000, v104
	v_lshlrev_b32_e32 v104, 16, v105
	v_and_b32_e32 v105, 0xffff0000, v105
	v_lshlrev_b32_e32 v116, 16, v106
	v_and_b32_e32 v117, 0xffff0000, v106
	v_lshlrev_b32_e32 v106, 16, v107
	v_and_b32_e32 v107, 0xffff0000, v107
	v_pk_fma_f32 v[64:65], s[14:15], v[64:65], v[104:105]
	v_pk_fma_f32 v[62:63], s[4:5], v[62:63], v[114:115]
	v_pk_fma_f32 v[104:105], s[14:15], v[60:61], v[106:107]
	v_mul_f32_e32 v60, v63, v63
	v_mul_f32_e32 v61, v65, v65
	v_pk_fma_f32 v[58:59], s[4:5], v[58:59], v[116:117]
	v_fmac_f32_e32 v60, v62, v62
	v_fmac_f32_e32 v61, v64, v64
	v_add_f32_e32 v60, v60, v61
	v_mul_f32_e32 v61, v59, v59
	v_fmac_f32_e32 v61, v58, v58
	v_add_f32_e32 v60, v61, v60
	v_mul_f32_e32 v61, v105, v105
	v_fmac_f32_e32 v61, v104, v104
	v_add_f32_e32 v106, v61, v60
	v_cvt_pk_bf16_f32 v60, v62, v63
	v_cvt_pk_bf16_f32 v62, v58, v59
	v_lshl_add_u64 v[58:59], s[8:9], 0, v[112:113]
	v_cvt_pk_bf16_f32 v61, v64, v65
	v_cvt_pk_bf16_f32 v63, v104, v105
	v_lshl_add_u64 v[58:59], v[154:155], 1, v[58:59]
	flat_store_dwordx4 v[58:59], v[60:63]
	v_lshlrev_b32_e32 v64, 16, v110
	v_and_b32_e32 v65, 0xffff0000, v110
	v_lshlrev_b32_e32 v60, 16, v108
	v_and_b32_e32 v61, 0xffff0000, v108
	v_lshlrev_b32_e32 v62, 16, v109
	v_and_b32_e32 v63, 0xffff0000, v109
	v_lshlrev_b32_e32 v104, 16, v111
	v_and_b32_e32 v105, 0xffff0000, v111
	v_pk_fma_f32 v[56:57], s[14:15], v[56:57], v[62:63]
	v_pk_fma_f32 v[54:55], s[4:5], v[54:55], v[60:61]
	v_pk_fma_f32 v[60:61], s[14:15], v[52:53], v[104:105]
	v_pk_fma_f32 v[52:53], s[4:5], v[50:51], v[64:65]
	v_mul_f32_e32 v50, v55, v55
	v_mul_f32_e32 v51, v57, v57
	v_fmac_f32_e32 v50, v54, v54
	v_fmac_f32_e32 v51, v56, v56
	v_add_f32_e32 v50, v50, v51
	v_mul_f32_e32 v51, v53, v53
	v_fmac_f32_e32 v51, v52, v52
	v_add_f32_e32 v50, v51, v50
	v_mul_f32_e32 v51, v61, v61
	v_fmac_f32_e32 v51, v60, v60
	v_add_f32_e32 v50, v51, v50
	v_add_f32_e32 v62, v106, v50
	v_cvt_pk_bf16_f32 v50, v54, v55
	v_cvt_pk_bf16_f32 v51, v56, v57
	v_cvt_pk_bf16_f32 v52, v52, v53
	v_cvt_pk_bf16_f32 v53, v60, v61
	flat_store_dwordx4 v[58:59], v[50:53] offset:256
	ds_bpermute_b32 v50, v178, v62
	s_waitcnt lgkmcnt(0)
	v_add_f32_e32 v50, v62, v50
	ds_bpermute_b32 v51, v177, v50
	s_and_saveexec_b64 s[24:25], vcc
	s_cbranch_execz .LBB0_2963
	v_lshlrev_b64 v[52:53], 6, v[102:103]
	v_lshl_add_u64 v[52:53], s[12:13], 0, v[52:53]
	v_lshl_add_u64 v[52:53], s[22:23], 2, v[52:53]
	s_lshl_b32 s96, s47, 2
	v_lshl_add_u64 v[52:53], v[52:53], 0, s[96:97]
	s_waitcnt lgkmcnt(0)
	v_add_f32_e32 v50, v50, v51
	flat_store_dword v[52:53], v50
